# GLA scan: low-rank rows prefetched straight into the gate-MFMA A fragment, output-tile flush remapped wave-local to the gate bytes, barrier between staging and gate section removed
# speedup vs baseline: 1.0071x; 1.0037x over previous
; __device__ __forceinline__ unsigned pk2(float lo, float hi) { f32x2_t v = {lo, hi}; bf16x2_t b = __builtin_convertvector(v, bf16x2_t); return __builtin_bit_cast(unsigned, b); }
; __device__ __forceinline__ void scan_unit(const int unit, const Args& a, unsigned char* lds, const int mk_wid) {
;     ...
;     { const int l_ = MK_TID & 63, r32 = l_ & 31, hi = l_ >> 5; const float* up = a.in[dir ? 12 : 10] + (size_t)(8 * hi) * 512 + h * 128 + (wid & 3) * 32 + r32;
;       v4u w; w.x = pk2(up[0], up[512]); w.y = pk2(up[2 * 512], up[3 * 512]); w.z = pk2(up[4 * 512], up[5 * 512]); w.w = pk2(up[6 * 512], up[7 * 512]);
;       upf = __builtin_bit_cast(bf16x8, w); biasc = a.in[dir ? 13 : 11][h * 128 + (wid & 3) * 32 + r32]; }
;     u16* qe = (u16*)(lds + L_QE); u16* ke = (u16*)(lds + L_KE); u16* am = (u16*)(lds + L_AM);
;     float* las = (float*)(lds + L_LAS); float* gs = (float*)(lds + L_GS); float* dl = (float*)(lds + L_DL);
;     const int ldsb = (int)(uintptr_t)lds;
;     u16* ot = (u16*)(lds + L_LAS);
;     int pend_cc = -1;
;     ...
;     f32x16 S[4]; S[0] = f32x16{}; S[1] = f32x16{}; S[2] = f32x16{}; S[3] = f32x16{};
;     bf16x8 qraw[2], kraw[2], vraw[4]; bf16x8 lraw = bf16x8{};
;     ...
;     GLA_LOAD(0);
;     ...
;           const bf16x8 af = *(const bf16x8*)(lds + L_LR + (tt * 32 + r32) * 32 + hi * 16);
.Lscan_qk_done2:
	v_mov_b32_e32 v128, 0
	v_mov_b32_e32 v129, 0
	v_mov_b32_e32 v130, 0
	v_mov_b32_e32 v131, 0
	v_mov_b32_e32 v132, 0
	v_mov_b32_e32 v133, 0
	v_mov_b32_e32 v134, 0
	v_mov_b32_e32 v135, 0
	v_mbcnt_lo_u32_b32 v66, -1, 0
	v_mbcnt_hi_u32_b32 v66, -1, v66
	v_bfe_u32 v67, v66, 4, 1
	v_lshlrev_b32_e32 v67, 3, v67
	v_bfe_u32 v68, v66, 2, 2
	v_add_u32_e32 v67, v67, v68
	s_and_b32 s96, s70, 3
	s_lshl_b32 s96, s96, 4
	v_add_u32_e32 v67, s96, v67
	v_lshrrev_b32_e32 v68, 5, v66
	v_lshlrev_b32_e32 v68, 6, v68
	v_and_b32_e32 v69, 3, v66
	v_lshl_add_u32 v68, v69, 4, v68
	s_lshr_b32 s96, s70, 2
	s_lshl_b32 s96, s96, 8
	v_add_u32_e32 v68, s96, v68
	v_sub_u32_e32 v69, 63, v67
	v_cndmask_b32_e64 v69, v69, v67, s[2:3]
	v_add_u32_e32 v69, s12, v69
	v_lshl_add_u32 v247, v69, 11, v68
	v_add_u32_e32 v248, 0x80, v247
	v_add_u32_e32 v67, 4, v67
	v_sub_u32_e32 v69, 63, v67
	v_cndmask_b32_e64 v69, v69, v67, s[2:3]
	v_add_u32_e32 v69, s12, v69
	v_lshl_add_u32 v249, v69, 11, v68
	v_add_u32_e32 v250, 0x80, v249
	v_mbcnt_lo_u32_b32 v66, -1, 0
	v_mbcnt_hi_u32_b32 v66, -1, v66
	s_lshr_b32 s96, s70, 2
	s_lshl_b32 s96, s96, 5
	v_and_b32_e32 v67, 31, v66
	v_add_u32_e32 v67, s96, v67
	v_sub_u32_e32 v68, 63, v67
	v_cndmask_b32_e64 v67, v68, v67, s[2:3]
	v_add_u32_e32 v67, s12, v67
	v_bfe_u32 v68, v66, 5, 1
	v_lshlrev_b32_e32 v68, 4, v68
	v_lshl_add_u32 v251, v67, 6, v68
	s_bitcmp1_b32 s8, 0
	s_cselect_b32 s97, 3, 0
	s_lshl_b32 s97, s97, 12
	v_add_u32_e32 v70, s97, v251
	v_mov_b32_e32 v71, 0
	v_lshl_add_u64 v[70:71], v[152:153], 0, v[70:71]
	global_load_dwordx4 v[96:99], v[70:71], off
	v_lshrrev_b32_e32 v67, 3, v66
	v_add_u32_e32 v67, s96, v67
	v_and_b32_e32 v68, 7, v66
	v_lshlrev_b32_e32 v68, 4, v68
	s_and_b32 s97, s70, 3
	s_lshl_b32 s97, s97, 7
	v_add_u32_e32 v68, s97, v68
	v_lshl_add_u32 v253, v67, 9, v68
	v_add_u32_e32 v253, s9, v253
	v_sub_u32_e32 v69, 63, v67
	v_cndmask_b32_e64 v67, v69, v67, s[2:3]
	v_lshl_add_u32 v252, v67, 11, v68

; __device__ __forceinline__ int crow(int r, int hi) { return (r & 3) + 8 * (r >> 2) + 4 * hi; }
; __device__ __forceinline__ int v_st(int k, int c) { const int kk = (k & ~0xC) | ((k & 4) << 1) | ((k & 8) >> 1); return ((kk >> 3) * 4 + (c >> 5)) * 512 + ((kk & 7) * 32 + (c & 31)) * 2; }
; #define OPAQUE_TID(name) int name = MK_TID; asm volatile("" : "+v"(name))
; __device__ __forceinline__ void scan_unit(const int unit, const Args& a, unsigned char* lds, const int mk_wid) {
;     ...
;           for (int p = 0; p < 4; ++p) { const int i_ = p * 16 + (t_ >> 5), c8 = t_ & 31; *(bf16x8*)(lds + L_V + (c8 >> 4) * 16384 + v_st(i_, (c8 & 15) * 8)) = vraw[p]; }
;           if (t_ < 128) *(bf16x8*)(lds + L_LR + (t_ >> 1) * 32 + (t_ & 1) * 16) = lraw; }
;         __syncthreads();
;         { OPAQUE_TID(t_); const int lane = t_ & 63, r32 = lane & 31, hi = lane >> 5; const int tt = wid >> 2, ct = wid & 3;
;           const bf16x8 af = *(const bf16x8*)(lds + L_LR + (tt * 32 + r32) * 32 + hi * 16);
;           const f32x16 z = __builtin_amdgcn_mfma_f32_32x32x16_bf16(af, upf, f32x16{}, 0, 0, 0);
;           float* lw = las + (tt * 32 + 4 * hi) * 128 + ct * 32 + r32;
; #pragma unroll
;           for (int r = 0; r < 16; ++r) { const float zz = z[r] + biasc;
;               lw[crow(r, 0) * 128] = (fminf(zz, 0.f) - __builtin_amdgcn_logf(1.f + __builtin_amdgcn_exp2f(-1.4426950408889634f * fabsf(zz))) * 0.6931471805599453f) * (1.f / 16.f); } }
.Lscan_nolrw:
	s_cmp_lt_i32 s34, 0
	s_cbranch_scc1 .Lscan_noflrd
	ds_read_b128 v[112:115], v253
	ds_read_b128 v[116:119], v253 offset:4096
	ds_read_b128 v[120:123], v253 offset:8192
	ds_read_b128 v[124:127], v253 offset:12288
.Lscan_noflrd:
	v_add_u32_e32 v66, s96, v247
	v_add_u32_e32 v67, s96, v248
	v_add_u32_e32 v68, s96, v249
	v_add_u32_e32 v69, s96, v250
	s_mov_b32 m0, s97
	s_nop 0
	global_load_lds_dwordx4 v66, s[16:17]
	s_add_i32 m0, s97, 0x400
	s_nop 0
	global_load_lds_dwordx4 v67, s[16:17]
	s_add_i32 m0, s97, 0x800
	s_nop 0
	global_load_lds_dwordx4 v68, s[16:17]
	s_add_i32 m0, s97, 0xc00
	s_nop 0
	global_load_lds_dwordx4 v69, s[16:17]
	s_cmp_lt_i32 s34, 0
	s_cbranch_scc1 .Lscan_noflush
	s_ashr_i32 s35, s34, 31
	s_lshl_b64 s[26:27], s[34:35], 6
	s_add_u32 s26, s26, s20
	s_addc_u32 s27, s27, s21
	s_add_u32 s26, s26, 0xffffff00
	s_addc_u32 s27, s27, -1
	s_lshl_b64 s[26:27], s[26:27], 11
	s_add_u32 s26, s26, s18
	s_addc_u32 s27, s27, s19
	s_movk_i32 s98, 0x4000
	s_movk_i32 s99, 0xc000
	s_bitcmp1_b32 s8, 0
	s_cselect_b32 s98, s99, s98
	v_add_u32_e32 v165, s98, v252
	v_add_u32_e32 v166, s98, v165
	v_add_u32_e32 v167, s98, v166
	s_waitcnt lgkmcnt(3)
	global_store_dwordx4 v252, v[112:115], s[26:27]
	s_waitcnt lgkmcnt(2)
	global_store_dwordx4 v165, v[116:119], s[26:27]
	s_waitcnt lgkmcnt(1)
	global_store_dwordx4 v166, v[120:123], s[26:27]
	s_waitcnt lgkmcnt(0)
	global_store_dwordx4 v167, v[124:127], s[26:27]
.Lscan_noflush:
	v_mbcnt_lo_u32_b32 v64, -1, 0
	v_mbcnt_hi_u32_b32 v64, -1, v64
	s_nop 0
	v_add_u32_e32 v64, s72, v64
	s_nop 0
	v_and_b32_e32 v68, 31, v64
	v_bfe_u32 v69, v64, 5, 1
	v_lshlrev_b32_e32 v69, 11, v69
	v_lshlrev_b32_e32 v68, 2, v68
	v_add3_u32 v80, s45, v69, v68
	v_mfma_f32_32x32x16_bf16 v[64:79], v[96:99], v[108:111], 0
	s_nop 11
	v_add_f32_e32 v64, v156, v64
	v_add_f32_e32 v65, v156, v65
	v_mul_f32_e64 v81, |v64|, s54
	v_mul_f32_e64 v82, |v65|, s54
	v_exp_f32_e32 v81, v81
	v_exp_f32_e32 v82, v82
	v_add_f32_e32 v66, v156, v66
	v_min_f32_e32 v64, 0, v64
	v_add_f32_e32 v81, 1.0, v81
	v_add_f32_e32 v82, 1.0, v82
	v_log_f32_e32 v81, v81
	v_log_f32_e32 v82, v82
	v_min_f32_e32 v65, 0, v65
	v_mul_f32_e64 v83, |v66|, s54
	v_fmac_f32_e32 v64, 0xbf317218, v81
	v_fmac_f32_e32 v65, 0xbf317218, v82
	v_add_f32_e32 v67, v156, v67
	v_exp_f32_e32 v83, v83
	v_mul_f32_e32 v64, 0x3db8aa3b, v64
	v_mul_f32_e32 v65, 0x3db8aa3b, v65
	ds_write2st64_b32 v80, v64, v65 offset1:2
	v_mul_f32_e64 v64, |v67|, s54
	v_exp_f32_e32 v64, v64
	v_add_f32_e32 v65, 1.0, v83
	v_log_f32_e32 v65, v65
	v_min_f32_e32 v66, 0, v66
	v_add_f32_e32 v64, 1.0, v64
	v_log_f32_e32 v64, v64
	v_fmac_f32_e32 v66, 0xbf317218, v65
	v_mul_f32_e32 v65, 0x3db8aa3b, v66
	v_min_f32_e32 v66, 0, v67
	v_fmac_f32_e32 v66, 0xbf317218, v64
	v_mul_f32_e32 v64, 0x3db8aa3b, v66
	ds_write2st64_b32 v80, v65, v64 offset0:4 offset1:6
	v_add_f32_e32 v64, v156, v68
	v_mul_f32_e64 v65, |v64|, s54
	v_add_f32_e32 v66, v156, v69
	v_exp_f32_e32 v65, v65
	v_mul_f32_e64 v67, |v66|, s54
	v_exp_f32_e32 v67, v67
	v_min_f32_e32 v64, 0, v64
	v_add_f32_e32 v65, 1.0, v65
	v_log_f32_e32 v65, v65
	v_add_f32_e32 v67, 1.0, v67
	v_log_f32_e32 v67, v67
	v_fmac_f32_e32 v64, 0xbf317218, v65
	v_min_f32_e32 v65, 0, v66
	v_fmac_f32_e32 v65, 0xbf317218, v67
	v_mul_f32_e32 v64, 0x3db8aa3b, v64
	v_mul_f32_e32 v65, 0x3db8aa3b, v65
	ds_write2st64_b32 v80, v64, v65 offset0:16 offset1:18
	v_add_f32_e32 v64, v156, v70
	v_mul_f32_e64 v65, |v64|, s54
	v_add_f32_e32 v66, v156, v71
	v_exp_f32_e32 v65, v65
	v_mul_f32_e64 v67, |v66|, s54
	v_exp_f32_e32 v67, v67
	v_min_f32_e32 v64, 0, v64
	v_add_f32_e32 v65, 1.0, v65
	v_log_f32_e32 v65, v65
	v_add_f32_e32 v67, 1.0, v67
	v_log_f32_e32 v67, v67
	v_fmac_f32_e32 v64, 0xbf317218, v65
	v_min_f32_e32 v65, 0, v66
	v_fmac_f32_e32 v65, 0xbf317218, v67
	v_mul_f32_e32 v64, 0x3db8aa3b, v64
	v_mul_f32_e32 v65, 0x3db8aa3b, v65
	ds_write2st64_b32 v80, v64, v65 offset0:20 offset1:22
	v_add_f32_e32 v64, v156, v72
	v_mul_f32_e64 v65, |v64|, s54
	v_add_f32_e32 v66, v156, v73
	v_exp_f32_e32 v65, v65
	v_mul_f32_e64 v67, |v66|, s54
	v_exp_f32_e32 v67, v67
	v_min_f32_e32 v64, 0, v64
	v_add_f32_e32 v65, 1.0, v65
	v_log_f32_e32 v65, v65
	v_add_f32_e32 v67, 1.0, v67
	v_log_f32_e32 v67, v67
	v_fmac_f32_e32 v64, 0xbf317218, v65
	v_min_f32_e32 v65, 0, v66
	v_fmac_f32_e32 v65, 0xbf317218, v67
	v_mul_f32_e32 v64, 0x3db8aa3b, v64
	v_mul_f32_e32 v65, 0x3db8aa3b, v65
	ds_write2st64_b32 v80, v64, v65 offset0:32 offset1:34
	v_add_f32_e32 v64, v156, v74
	v_mul_f32_e64 v65, |v64|, s54
	v_add_f32_e32 v66, v156, v75
	v_exp_f32_e32 v65, v65
	v_mul_f32_e64 v67, |v66|, s54
	v_exp_f32_e32 v67, v67
	v_min_f32_e32 v64, 0, v64
	v_add_f32_e32 v65, 1.0, v65
	v_log_f32_e32 v65, v65
	v_add_f32_e32 v67, 1.0, v67
	v_log_f32_e32 v67, v67
	v_fmac_f32_e32 v64, 0xbf317218, v65
	v_min_f32_e32 v65, 0, v66
	v_fmac_f32_e32 v65, 0xbf317218, v67
	v_mul_f32_e32 v64, 0x3db8aa3b, v64
	v_mul_f32_e32 v65, 0x3db8aa3b, v65
	ds_write2st64_b32 v80, v64, v65 offset0:36 offset1:38
	v_add_f32_e32 v64, v156, v76
	v_mul_f32_e64 v65, |v64|, s54
	v_add_f32_e32 v66, v156, v77
	v_exp_f32_e32 v65, v65
	v_mul_f32_e64 v67, |v66|, s54
	v_exp_f32_e32 v67, v67
	v_min_f32_e32 v64, 0, v64
	v_add_f32_e32 v65, 1.0, v65
	v_log_f32_e32 v65, v65
	v_add_f32_e32 v67, 1.0, v67
	v_log_f32_e32 v67, v67
	v_fmac_f32_e32 v64, 0xbf317218, v65
	v_min_f32_e32 v65, 0, v66
	v_fmac_f32_e32 v65, 0xbf317218, v67
	v_mul_f32_e32 v64, 0x3db8aa3b, v64
	v_mul_f32_e32 v65, 0x3db8aa3b, v65
	ds_write2st64_b32 v80, v64, v65 offset0:48 offset1:50
	v_add_f32_e32 v64, v156, v78
	v_mul_f32_e64 v65, |v64|, s54
	v_add_f32_e32 v66, v156, v79
	v_exp_f32_e32 v65, v65
	v_mul_f32_e64 v67, |v66|, s54
	v_exp_f32_e32 v67, v67
	v_min_f32_e32 v64, 0, v64
	v_add_f32_e32 v65, 1.0, v65
	v_log_f32_e32 v65, v65
	v_add_f32_e32 v67, 1.0, v67
	v_log_f32_e32 v67, v67
	v_fmac_f32_e32 v64, 0xbf317218, v65
	v_min_f32_e32 v65, 0, v66
	v_fmac_f32_e32 v65, 0xbf317218, v67
	v_mul_f32_e32 v64, 0x3db8aa3b, v64
	v_mul_f32_e32 v65, 0x3db8aa3b, v65
	ds_write2st64_b32 v80, v64, v65 offset0:52 offset1:54
	s_waitcnt lgkmcnt(0)
	s_barrier
; __device__ __forceinline__ int v_st(int k, int c) { const int kk = (k & ~0xC) | ((k & 4) << 1) | ((k & 8) >> 1); return ((kk >> 3) * 4 + (c >> 5)) * 512 + ((kk & 7) * 32 + (c & 31)) * 2; }
; __device__ __forceinline__ float bf2f(short s) { return __uint_as_float(((unsigned)(unsigned short)s) << 16); }
; __device__ __forceinline__ float bf2f(u16 u) { return __uint_as_float((unsigned)u << 16); }
; #define OPAQUE_TID(name) int name = MK_TID; asm volatile("" : "+v"(name))
; __device__ __forceinline__ void scan_unit(const int unit, const Args& a, unsigned char* lds, const int mk_wid) {
;     ...
;         { OPAQUE_TID(t_); const int c = t_ & 127, g = t_ >> 7;
;           float bl[16]; float run = 0.f;
;           { const float* lp = las + (g * 16) * 128 + c;
; #pragma unroll
;             for (int ii = 0; ii < 16; ++ii) { run += lp[ii * 128]; bl[ii] = run; } }
;           gs[g * 128 + c] = run;
;           __syncthreads();
;           const float g0 = gs[c], g1 = gs[128 + c], g2 = gs[256 + c], g3 = gs[384 + c];
;           const float off = (g > 0 ? g0 : 0.f) + (g > 1 ? g1 : 0.f) + (g > 2 ? g2 : 0.f);
;           const float btot = (g0 + g1) + (g2 + g3);
;           const float dlc = __builtin_amdgcn_exp2f(btot * 1.4426950408889634f);
;           if (g == 0) dl[c] = dlc;
;           u16* qcol = qe + (g * 16) * QP + c; u16* kcol = ke + (g * 16) * QP + c; unsigned char* kdb = lds + L_KD + v_st(g * 16, c);
; #pragma unroll
;           for (int ii = 0; ii < 16; ++ii) { const float bb = bl[ii] + off;
;               const float qf = bf2f(qcol[ii * QP]), kf = bf2f(kcol[ii * QP]);
;               const float e = __builtin_amdgcn_exp2f(bb * 1.4426950408889634f), ker = kf * __builtin_amdgcn_rcpf(e);
	v_mbcnt_lo_u32_b32 v64, -1, 0
	v_mbcnt_hi_u32_b32 v64, -1, v64
	s_lshl_b32 s96, s70, 12
	s_add_i32 s96, s96, s9
	v_lshl_add_u32 v65, v64, 3, s96
	ds_read_b64 v[170:171], v65
	ds_read_b64 v[172:173], v65 offset:512
	ds_read_b64 v[174:175], v65 offset:1024
	ds_read_b64 v[176:177], v65 offset:1536
	ds_read_b64 v[178:179], v65 offset:2048
	ds_read_b64 v[180:181], v65 offset:2560
	ds_read_b64 v[182:183], v65 offset:3072
	ds_read_b64 v[184:185], v65 offset:3584
	s_cmp_gt_u32 s70, 0
	s_cselect_b32 s97, 1.0, 0
	v_mov_b32_e32 v238, s97
	s_cmp_gt_u32 s70, 1
	s_cselect_b32 s97, 1.0, 0
	v_mov_b32_e32 v239, s97
	s_cmp_gt_u32 s70, 2
	s_cselect_b32 s97, 1.0, 0
	v_mov_b32_e32 v240, s97
	s_cmp_gt_u32 s70, 3
	s_cselect_b32 s97, 1.0, 0
	v_mov_b32_e32 v241, s97
	s_cmp_gt_u32 s70, 4
	s_cselect_b32 s97, 1.0, 0
	v_mov_b32_e32 v242, s97
	s_cmp_gt_u32 s70, 5
	s_cselect_b32 s97, 1.0, 0
	v_mov_b32_e32 v243, s97
	s_cmp_gt_u32 s70, 6
	s_cselect_b32 s97, 1.0, 0
	v_mov_b32_e32 v244, s97
	s_lshl_b32 s98, s70, 9
	s_add_i32 s98, s98, 0x20000
	v_lshl_add_u32 v66, v64, 3, s98
	v_lshlrev_b32_e32 v67, 3, v64
	v_add_u32_e32 v67, 0x20000, v67
	s_mul_i32 s99, s70, 0x880
	v_lshl_add_u32 v68, v64, 2, s99
	v_and_b32_e32 v94, 2, v64
	v_lshlrev_b32_e32 v94, 1, v94
	v_and_b32_e32 v95, 4, v64
	v_lshrrev_b32_e32 v95, 1, v95
	v_and_b32_e32 v70, 0xfffffff9, v64
	v_or3_b32 v94, v94, v95, v70
	v_lshl_add_u32 v94, v94, 2, s99
	s_lshr_b32 s98, s70, 1
	s_lshl_b32 s98, s98, 12
	s_and_b32 s99, s70, 1
	s_lshl_b32 s99, s99, 8
	s_add_i32 s98, s98, s99
	v_lshrrev_b32_e32 v69, 4, v64
	v_lshlrev_b32_e32 v69, 9, v69
	v_and_b32_e32 v70, 15, v64
	v_lshl_add_u32 v69, v70, 2, v69
	v_add_u32_e32 v69, s98, v69
	s_waitcnt lgkmcnt(7)
	v_add_f32_e32 v170, 0, v170
	v_add_f32_e32 v171, 0, v171
	s_waitcnt lgkmcnt(6)
	v_add_f32_e32 v172, v170, v172
	v_add_f32_e32 v173, v171, v173
	s_waitcnt lgkmcnt(5)
	v_add_f32_e32 v174, v172, v174
	v_add_f32_e32 v175, v173, v175
	s_waitcnt lgkmcnt(4)
	v_add_f32_e32 v176, v174, v176
	v_add_f32_e32 v177, v175, v177
	s_waitcnt lgkmcnt(3)
	v_add_f32_e32 v178, v176, v178
	v_add_f32_e32 v179, v177, v179
	s_waitcnt lgkmcnt(2)
	v_add_f32_e32 v180, v178, v180
	v_add_f32_e32 v181, v179, v181
	s_waitcnt lgkmcnt(1)
	v_add_f32_e32 v182, v180, v182
	v_add_f32_e32 v183, v181, v183
	s_waitcnt lgkmcnt(0)
	v_add_f32_e32 v184, v182, v184
	v_add_f32_e32 v185, v183, v185
	ds_write_b64 v66, v[184:185]
	s_waitcnt lgkmcnt(0)
	s_barrier
	ds_read_b64 v[72:73], v67
	ds_read_b64 v[74:75], v67 offset:512
	ds_read_b64 v[76:77], v67 offset:1024
	ds_read_b64 v[78:79], v67 offset:1536
	ds_read_b64 v[80:81], v67 offset:2048
	ds_read_b64 v[82:83], v67 offset:2560
	ds_read_b64 v[84:85], v67 offset:3072
	ds_read_b64 v[86:87], v67 offset:3584
	s_waitcnt lgkmcnt(0)
	v_mul_f32_e32 v88, v238, v72
	v_mul_f32_e32 v89, v238, v73
	v_fmac_f32_e32 v88, v239, v74
	v_fmac_f32_e32 v89, v239, v75
	v_fmac_f32_e32 v88, v240, v76
	v_fmac_f32_e32 v89, v240, v77
	v_fmac_f32_e32 v88, v241, v78
	v_fmac_f32_e32 v89, v241, v79
	v_fmac_f32_e32 v88, v242, v80
	v_fmac_f32_e32 v89, v242, v81
	v_fmac_f32_e32 v88, v243, v82
	v_fmac_f32_e32 v89, v243, v83
	v_fmac_f32_e32 v88, v244, v84
	v_fmac_f32_e32 v89, v244, v85
	v_add_f32_e32 v90, v72, v74
	v_add_f32_e32 v91, v73, v75
	v_add_f32_e32 v90, v90, v76
	v_add_f32_e32 v91, v91, v77
	v_add_f32_e32 v90, v90, v78
	v_add_f32_e32 v91, v91, v79
	v_add_f32_e32 v90, v90, v80
	v_add_f32_e32 v91, v91, v81
	v_add_f32_e32 v90, v90, v82
	v_add_f32_e32 v91, v91, v83
	v_add_f32_e32 v90, v90, v84
	v_add_f32_e32 v91, v91, v85
	v_add_f32_e32 v90, v90, v86
	v_add_f32_e32 v91, v91, v87
	v_mov_b32_e32 v92, v90
	v_mov_b32_e32 v93, v91
	v_exp_f32_e32 v92, v92
	v_exp_f32_e32 v93, v93
	v_add_f32_e32 v170, v170, v88
	v_add_f32_e32 v171, v171, v89
	v_add_f32_e32 v172, v172, v88
	v_add_f32_e32 v173, v173, v89
	v_add_f32_e32 v174, v174, v88
	v_add_f32_e32 v175, v175, v89
	v_add_f32_e32 v176, v176, v88
	v_add_f32_e32 v177, v177, v89
	v_add_f32_e32 v178, v178, v88
	v_add_f32_e32 v179, v179, v89
	v_add_f32_e32 v180, v180, v88
	v_add_f32_e32 v181, v181, v89
	v_add_f32_e32 v182, v182, v88
	v_add_f32_e32 v183, v183, v89
	v_add_f32_e32 v184, v184, v88
	v_add_f32_e32 v185, v185, v89
	v_exp_f32_e32 v170, v170
	v_exp_f32_e32 v171, v171
	v_exp_f32_e32 v172, v172
	v_exp_f32_e32 v173, v173
	v_exp_f32_e32 v174, v174
	v_exp_f32_e32 v175, v175
	v_exp_f32_e32 v176, v176
	v_exp_f32_e32 v177, v177
	v_exp_f32_e32 v178, v178
	v_exp_f32_e32 v179, v179
	v_exp_f32_e32 v180, v180
	v_exp_f32_e32 v181, v181
	v_exp_f32_e32 v182, v182
	v_exp_f32_e32 v183, v183
	v_exp_f32_e32 v184, v184
	v_exp_f32_e32 v185, v185
	v_rcp_f32_e32 v186, v170
	v_rcp_f32_e32 v187, v171
	v_rcp_f32_e32 v188, v172
	v_rcp_f32_e32 v189, v173
	v_rcp_f32_e32 v190, v174
	v_rcp_f32_e32 v191, v175
	v_rcp_f32_e32 v192, v176
	v_rcp_f32_e32 v193, v177
	v_rcp_f32_e32 v194, v178
	v_rcp_f32_e32 v195, v179
	v_rcp_f32_e32 v196, v180
	v_rcp_f32_e32 v197, v181
	v_rcp_f32_e32 v198, v182
	v_rcp_f32_e32 v199, v183
	v_rcp_f32_e32 v200, v184
	v_rcp_f32_e32 v201, v185
	v_mul_f32_e32 v170, 0x3db504f3, v170
	v_mul_f32_e32 v171, 0x3db504f3, v171
	v_mul_f32_e32 v172, 0x3db504f3, v172
	v_mul_f32_e32 v173, 0x3db504f3, v173
	v_mul_f32_e32 v174, 0x3db504f3, v174
	v_mul_f32_e32 v175, 0x3db504f3, v175
	v_mul_f32_e32 v176, 0x3db504f3, v176
	v_mul_f32_e32 v177, 0x3db504f3, v177
	v_mul_f32_e32 v178, 0x3db504f3, v178
	v_mul_f32_e32 v179, 0x3db504f3, v179
	v_mul_f32_e32 v180, 0x3db504f3, v180
	v_mul_f32_e32 v181, 0x3db504f3, v181
	v_mul_f32_e32 v182, 0x3db504f3, v182
	v_mul_f32_e32 v183, 0x3db504f3, v183
	v_mul_f32_e32 v184, 0x3db504f3, v184
	v_mul_f32_e32 v185, 0x3db504f3, v185
	s_cmp_lg_u32 s70, 0
	s_cbranch_scc1 .Lscan_c2_nodl
	v_lshlrev_b32_e32 v70, 3, v64
	v_add_u32_e32 v70, 0x1fc00, v70
	ds_write_b64 v70, v[92:93]

.Lscan_pf_v:
	v_add_u32_e32 v70, s35, v251
	v_mov_b32_e32 v71, 0
	v_lshl_add_u64 v[70:71], v[152:153], 0, v[70:71]
	global_load_dwordx4 v[96:99], v[70:71], off
